# pass A next-unit gathers: SGPR-base + 32-bit lane offset addressing (SALU row bases) instead of per-load 64-bit VGPR address arithmetic
# baseline (speedup 1.0000x reference)
.LBB0_784:
	s_cmpk_gt_i32 s79, 0xfff
	s_waitcnt lgkmcnt(0)
	s_barrier
	s_cbranch_scc1 .LBB0_789
	s_and_b32 s4, s79, 0x7f
	s_ashr_i32 s0, s79, 11
	s_ashr_i32 s1, s0, 31
	s_lshl_b32 s5, s4, 6
	s_lshl_b64 s[0:1], s[0:1], 13
	s_add_i32 s5, s5, s33
	s_add_u32 s6, s0, s5
	s_addc_u32 s7, s1, 0
	s_lshr_b32 s0, s79, 1
	s_and_b32 s0, s0, 0x3c0
	v_add_u32_e32 v0, s0, v207
	s_mul_i32 s0, s7, 0x3c00
	s_mul_hi_u32 s1, s6, 0x3c00
	s_add_i32 s1, s1, s0
	s_mul_i32 s0, s6, 0x3c00
	v_readlane_b32 s8, v233, 14
	v_readlane_b32 s9, v233, 15
	v_lshlrev_b32_e32 v1, 1, v0
	v_add_u32_e32 v2, 0x1000, v1
	s_add_u32 s0, s8, s0
	s_addc_u32 s1, s9, s1
	s_lshl_b64 s[6:7], s[6:7], 11
	v_readlane_b32 s8, v233, 24
	v_readlane_b32 s9, v233, 25
	v_lshlrev_b32_e32 v4, 2, v0
	v_add_u32_e32 v5, 0x1000, v4
	s_add_u32 s90, s2, s6
	s_addc_u32 s91, s3, s7
	s_add_u32 s92, s8, s6
	s_addc_u32 s93, s9, s7
	v_add_u32_e32 v6, 0x2000, v4
	global_load_ushort v37, v1, s[0:1]
	global_load_ushort v27, v1, s[0:1] offset:2048
	global_load_ushort v45, v2, s[0:1]
	global_load_ushort v36, v1, s[90:91]
	global_load_ushort v25, v1, s[92:93]
	s_add_u32 s94, s0, 0x3c00
	s_addc_u32 s95, s1, 0
	global_load_ushort v39, v1, s[94:95]
	global_load_ushort v38, v1, s[94:95] offset:2048
	global_load_ushort v47, v2, s[94:95]
	global_load_ushort v41, v1, s[90:91] offset:2048
	global_load_ushort v40, v1, s[92:93] offset:2048
	s_add_u32 s94, s0, 0x7800
	s_addc_u32 s95, s1, 0
	s_add_u32 s90, s90, 0x1000
	s_addc_u32 s91, s91, 0
	s_add_u32 s92, s92, 0x1000
	s_addc_u32 s93, s93, 0
	global_load_ushort v46, v1, s[94:95]
	global_load_ushort v43, v1, s[94:95] offset:2048
	global_load_ushort v52, v2, s[94:95]
	global_load_ushort v44, v1, s[90:91]
	global_load_ushort v42, v1, s[92:93]
	s_add_u32 s94, s0, 0xb400
	s_addc_u32 s95, s1, 0
	global_load_ushort v48, v1, s[94:95]
	global_load_ushort v50, v1, s[94:95] offset:2048
	global_load_ushort v54, v2, s[94:95]
	global_load_ushort v51, v1, s[90:91] offset:2048
	global_load_ushort v49, v1, s[92:93] offset:2048
	s_add_u32 s94, s0, 0xf000
	s_addc_u32 s95, s1, 0
	s_add_u32 s90, s90, 0x1000
	s_addc_u32 s91, s91, 0
	s_add_u32 s92, s92, 0x1000
	s_addc_u32 s93, s93, 0
	global_load_ushort v55, v1, s[94:95]
	global_load_ushort v53, v1, s[94:95] offset:2048
	global_load_ushort v56, v2, s[94:95]
	global_load_ushort v57, v1, s[90:91]
	global_load_ushort v58, v1, s[92:93]
	s_add_u32 s94, s0, 0x12c00
	s_addc_u32 s95, s1, 0
	global_load_ushort v62, v1, s[94:95]
	global_load_ushort v59, v1, s[94:95] offset:2048
	global_load_ushort v61, v2, s[94:95]
	global_load_ushort v63, v1, s[90:91] offset:2048
	global_load_ushort v60, v1, s[92:93] offset:2048
	s_add_u32 s94, s0, 0x16800
	s_addc_u32 s95, s1, 0
	s_add_u32 s90, s90, 0x1000
	s_addc_u32 s91, s91, 0
	s_add_u32 s92, s92, 0x1000
	s_addc_u32 s93, s93, 0
	global_load_ushort v64, v1, s[94:95]
	global_load_ushort v65, v1, s[94:95] offset:2048
	global_load_ushort v66, v2, s[94:95]
	global_load_ushort v68, v1, s[90:91]
	global_load_ushort v67, v1, s[92:93]
	s_add_u32 s94, s0, 0x1a400
	s_addc_u32 s95, s1, 0
	global_load_ushort v72, v1, s[94:95]
	global_load_ushort v70, v1, s[94:95] offset:2048
	global_load_ushort v71, v2, s[94:95]
	global_load_ushort v74, v1, s[90:91] offset:2048
	global_load_ushort v73, v1, s[92:93] offset:2048
	v_readlane_b32 s5, v233, 5
	s_or_b32 s4, s4, s5
	s_cmp_eq_u32 s4, 0
	s_cbranch_scc1 .LBB0_787
	s_add_u32 s0, s0, 0xffffc400
	s_addc_u32 s1, s1, -1
	global_load_ushort v75, v1, s[0:1]
	global_load_ushort v76, v1, s[0:1] offset:2048
	global_load_ushort v88, v2, s[0:1]
	s_branch .LBB0_788

.LBB0_788:
	global_load_dword v84, v4, s[40:41]
	global_load_dword v22, v5, s[40:41]
	global_load_dword v24, v6, s[40:41]
	s_load_dwordx2 s[0:1], s[82:83], 0x98
	global_load_dword v85, v4, s[12:13]
	global_load_dword v26, v4, s[14:15]
	s_waitcnt lgkmcnt(0)
	global_load_dword v86, v4, s[0:1]
